# ATTN fast tail: next K/V tile ds_write moved from step end to mid-step (after 2nd PV chunk), lgkm counts adjusted
# baseline (speedup 1.0000x reference)
.Lfa_norescale:
	v_fmamk_f32 v0, v0, 0x3fb8aa3b, v36
	v_fmamk_f32 v1, v1, 0x3fb8aa3b, v36
	v_fmamk_f32 v2, v2, 0x3fb8aa3b, v36
	v_fmamk_f32 v3, v3, 0x3fb8aa3b, v36
	v_fmamk_f32 v4, v4, 0x3fb8aa3b, v36
	v_fmamk_f32 v5, v5, 0x3fb8aa3b, v36
	v_fmamk_f32 v6, v6, 0x3fb8aa3b, v36
	v_fmamk_f32 v7, v7, 0x3fb8aa3b, v36
	v_exp_f32_e32 v0, v0
	v_exp_f32_e32 v1, v1
	v_add_f32_e32 v37, v0, v37
	v_exp_f32_e32 v2, v2
	v_add_f32_e32 v37, v1, v37
	v_exp_f32_e32 v3, v3
	v_add_f32_e32 v37, v2, v37
	v_exp_f32_e32 v4, v4
	v_add_f32_e32 v37, v3, v37
	v_exp_f32_e32 v5, v5
	v_add_f32_e32 v37, v4, v37
	v_exp_f32_e32 v6, v6
	v_add_f32_e32 v37, v5, v37
	v_exp_f32_e32 v7, v7
	v_add_f32_e32 v37, v6, v37
	s_nop 0
	v_add_f32_e32 v37, v7, v37
	v_cvt_pk_bf16_f32 v0, v0, v1
	v_cvt_pk_bf16_f32 v1, v2, v3
	v_cvt_pk_bf16_f32 v2, v4, v5
	v_cvt_pk_bf16_f32 v3, v6, v7
	s_waitcnt lgkmcnt(14)
	s_nop 0
	v_mfma_f32_32x32x16_bf16 v[64:79], v[134:137], v[0:3], v[64:79]
	s_waitcnt lgkmcnt(12)
	v_mfma_f32_32x32x16_bf16 v[48:63], v[138:141], v[0:3], v[48:63]
	v_fmamk_f32 v8, v8, 0x3fb8aa3b, v36
	v_fmamk_f32 v9, v9, 0x3fb8aa3b, v36
	v_fmamk_f32 v10, v10, 0x3fb8aa3b, v36
	v_fmamk_f32 v11, v11, 0x3fb8aa3b, v36
	v_fmamk_f32 v12, v12, 0x3fb8aa3b, v36
	v_fmamk_f32 v13, v13, 0x3fb8aa3b, v36
	v_fmamk_f32 v14, v14, 0x3fb8aa3b, v36
	v_fmamk_f32 v15, v15, 0x3fb8aa3b, v36
	v_exp_f32_e32 v8, v8
	v_exp_f32_e32 v9, v9
	v_add_f32_e32 v37, v8, v37
	v_exp_f32_e32 v10, v10
	v_add_f32_e32 v37, v9, v37
	v_exp_f32_e32 v11, v11
	v_add_f32_e32 v37, v10, v37
	v_exp_f32_e32 v12, v12
	v_add_f32_e32 v37, v11, v37
	v_exp_f32_e32 v13, v13
	v_add_f32_e32 v37, v12, v37
	v_exp_f32_e32 v14, v14
	v_add_f32_e32 v37, v13, v37
	v_exp_f32_e32 v15, v15
	v_add_f32_e32 v37, v14, v37
	s_nop 0
	v_add_f32_e32 v37, v15, v37
	v_cvt_pk_bf16_f32 v8, v8, v9
	v_cvt_pk_bf16_f32 v9, v10, v11
	v_cvt_pk_bf16_f32 v10, v12, v13
	v_cvt_pk_bf16_f32 v11, v14, v15
	s_waitcnt lgkmcnt(10)
	s_nop 0
	v_mfma_f32_32x32x16_bf16 v[64:79], v[142:145], v[8:11], v[64:79]
	s_waitcnt lgkmcnt(8)
	v_mfma_f32_32x32x16_bf16 v[48:63], v[146:149], v[8:11], v[48:63]
	s_andn2_b64 vcc, exec, s[30:31]
	s_cbranch_vccnz .Lfa_nw
	s_xor_b32 s0, s36, 1
	s_mulk_i32 s0, 0x2400
	v_add_u32_e32 v252, s0, v195
	s_xor_b32 s0, s36, 3
	s_mulk_i32 s0, 0x2400
	v_add_u32_e32 v253, s0, v195
	s_waitcnt vmcnt(0)
	ds_write_b128 v252, v[96:99]
	ds_write_b128 v253, v[100:103]
	s_branch .Lfa_wrdone

.Lfa_wrdone:
	v_fmamk_f32 v16, v16, 0x3fb8aa3b, v36
	v_fmamk_f32 v17, v17, 0x3fb8aa3b, v36
	v_fmamk_f32 v18, v18, 0x3fb8aa3b, v36
	v_fmamk_f32 v19, v19, 0x3fb8aa3b, v36
	v_fmamk_f32 v20, v20, 0x3fb8aa3b, v36
	v_fmamk_f32 v21, v21, 0x3fb8aa3b, v36
	v_fmamk_f32 v22, v22, 0x3fb8aa3b, v36
	v_fmamk_f32 v23, v23, 0x3fb8aa3b, v36
	v_exp_f32_e32 v16, v16
	v_exp_f32_e32 v17, v17
	v_add_f32_e32 v37, v16, v37
	v_exp_f32_e32 v18, v18
	v_add_f32_e32 v37, v17, v37
	v_exp_f32_e32 v19, v19
	v_add_f32_e32 v37, v18, v37
	v_exp_f32_e32 v20, v20
	v_add_f32_e32 v37, v19, v37
	v_exp_f32_e32 v21, v21
	v_add_f32_e32 v37, v20, v37
	v_exp_f32_e32 v22, v22
	v_add_f32_e32 v37, v21, v37
	v_exp_f32_e32 v23, v23
	v_add_f32_e32 v37, v22, v37
	s_nop 0
	v_add_f32_e32 v37, v23, v37
	v_cvt_pk_bf16_f32 v16, v16, v17
	v_cvt_pk_bf16_f32 v17, v18, v19
	v_cvt_pk_bf16_f32 v18, v20, v21
	v_cvt_pk_bf16_f32 v19, v22, v23
	s_waitcnt lgkmcnt(8)
	s_nop 0
	v_mfma_f32_32x32x16_bf16 v[64:79], v[236:239], v[16:19], v[64:79]
	s_waitcnt lgkmcnt(6)
	v_mfma_f32_32x32x16_bf16 v[48:63], v[240:243], v[16:19], v[48:63]
	v_fmamk_f32 v24, v24, 0x3fb8aa3b, v36
	v_fmamk_f32 v25, v25, 0x3fb8aa3b, v36
	v_fmamk_f32 v26, v26, 0x3fb8aa3b, v36
	v_fmamk_f32 v27, v27, 0x3fb8aa3b, v36
	v_fmamk_f32 v28, v28, 0x3fb8aa3b, v36
	v_fmamk_f32 v29, v29, 0x3fb8aa3b, v36
	v_fmamk_f32 v30, v30, 0x3fb8aa3b, v36
	v_fmamk_f32 v31, v31, 0x3fb8aa3b, v36
	v_exp_f32_e32 v24, v24
	v_exp_f32_e32 v25, v25
	v_add_f32_e32 v37, v24, v37
	v_exp_f32_e32 v26, v26
	v_add_f32_e32 v37, v25, v37
	v_exp_f32_e32 v27, v27
	v_add_f32_e32 v37, v26, v37
	v_exp_f32_e32 v28, v28
	v_add_f32_e32 v37, v27, v37
	v_exp_f32_e32 v29, v29
	v_add_f32_e32 v37, v28, v37
	v_exp_f32_e32 v30, v30
	v_add_f32_e32 v37, v29, v37
	v_exp_f32_e32 v31, v31
	v_add_f32_e32 v37, v30, v37
	s_nop 0
	v_add_f32_e32 v37, v31, v37
	v_cvt_pk_bf16_f32 v24, v24, v25
	v_cvt_pk_bf16_f32 v25, v26, v27
	v_cvt_pk_bf16_f32 v26, v28, v29
	v_cvt_pk_bf16_f32 v27, v30, v31
	s_waitcnt lgkmcnt(4)
	s_nop 0
	v_mfma_f32_32x32x16_bf16 v[64:79], v[244:247], v[24:27], v[64:79]
	s_waitcnt lgkmcnt(2)
	v_mfma_f32_32x32x16_bf16 v[48:63], v[248:251], v[24:27], v[48:63]
	v_fmac_f32_e32 v37, v121, v34
	v_mov_b32_e32 v123, v33
	v_mov_b32_e32 v121, v37
	s_branch .LBB0_1472
